# stack10 + grid barrier: non-leader workgroups poll the top-level generation word directly (one relay hop less)
# speedup vs baseline: 1.0087x; 1.0028x over previous
.LBB1_179:
	v_readlane_b32 s6, v254, 21
	v_readlane_b32 s7, v254, 22
	v_cvt_f32_u32_e32 v1, v2
	v_sub_u32_e32 v4, 0, v2
	v_rcp_iflag_f32_e32 v1, v1
	s_nop 1
	global_atomic_add v3, v113, v215, s[6:7] sc0
	v_mul_f32_e32 v1, 0x4f7ffffe, v1
	v_cvt_u32_f32_e32 v1, v1
	v_mul_lo_u32 v4, v4, v1
	v_mul_hi_u32 v4, v1, v4
	v_add_u32_e32 v1, v1, v4
	s_waitcnt vmcnt(0)
	v_mul_hi_u32 v1, v3, v1
	v_mul_lo_u32 v4, v1, v2
	v_sub_u32_e32 v4, v3, v4
	v_add_u32_e32 v5, 1, v1
	v_cmp_ge_u32_e32 vcc, v4, v2
	v_add_u32_e32 v3, 1, v3
	s_nop 0
	v_cndmask_b32_e32 v1, v1, v5, vcc
	v_sub_u32_e32 v5, v4, v2
	v_cndmask_b32_e32 v4, v4, v5, vcc
	v_add_u32_e32 v5, 1, v1
	v_cmp_ge_u32_e32 vcc, v4, v2
	s_nop 1
	v_cndmask_b32_e32 v1, v1, v5, vcc
	v_mul_lo_u32 v4, v2, v1
	v_add_u32_e32 v2, v4, v2
	v_cmp_ne_u32_e32 vcc, v3, v2
	s_and_saveexec_b64 s[6:7], vcc
	s_xor_b64 s[16:17], exec, s[6:7]
	s_cbranch_execz .LBB1_193
	v_readlane_b32 s6, v254, 27
	v_readlane_b32 s7, v254, 28
	s_waitcnt lgkmcnt(0)
	s_nop 3
	global_load_dword v0, v113, s[6:7] sc1
	s_waitcnt vmcnt(0)
	v_cmp_eq_u32_e32 vcc, v0, v1
	s_and_saveexec_b64 s[18:19], vcc
	s_cbranch_execz .LBB1_192
	s_mov_b32 s5, 1
	s_mov_b64 s[26:27], 0
	s_branch .LBB1_183

.LBB1_185:
	v_readlane_b32 s6, v254, 27
	v_readlane_b32 s7, v254, 28
	s_add_i32 s5, s5, 1
	s_mov_b64 s[38:39], -1
	s_nop 2
	global_load_dword v0, v113, s[6:7] sc1
	s_waitcnt vmcnt(0)
	v_cmp_ne_u32_e32 vcc, v0, v1
	s_orn2_b64 s[36:37], vcc, exec
	s_branch .LBB1_182

.LBB1_312:
	v_readlane_b32 s6, v254, 21
	v_readlane_b32 s7, v254, 22
	v_cvt_f32_u32_e32 v1, v2
	v_sub_u32_e32 v4, 0, v2
	v_rcp_iflag_f32_e32 v1, v1
	s_nop 1
	global_atomic_add v3, v113, v215, s[6:7] sc0
	v_mul_f32_e32 v1, 0x4f7ffffe, v1
	v_cvt_u32_f32_e32 v1, v1
	v_mul_lo_u32 v4, v4, v1
	v_mul_hi_u32 v4, v1, v4
	v_add_u32_e32 v1, v1, v4
	s_waitcnt vmcnt(0)
	v_mul_hi_u32 v1, v3, v1
	v_mul_lo_u32 v4, v1, v2
	v_sub_u32_e32 v4, v3, v4
	v_add_u32_e32 v5, 1, v1
	v_cmp_ge_u32_e32 vcc, v4, v2
	v_add_u32_e32 v3, 1, v3
	s_nop 0
	v_cndmask_b32_e32 v1, v1, v5, vcc
	v_sub_u32_e32 v5, v4, v2
	v_cndmask_b32_e32 v4, v4, v5, vcc
	v_add_u32_e32 v5, 1, v1
	v_cmp_ge_u32_e32 vcc, v4, v2
	s_nop 1
	v_cndmask_b32_e32 v1, v1, v5, vcc
	v_mul_lo_u32 v4, v2, v1
	v_add_u32_e32 v2, v4, v2
	v_cmp_ne_u32_e32 vcc, v3, v2
	s_and_saveexec_b64 s[6:7], vcc
	s_xor_b64 s[18:19], exec, s[6:7]
	s_cbranch_execz .LBB1_326
	v_readlane_b32 s6, v254, 27
	v_readlane_b32 s7, v254, 28
	s_waitcnt lgkmcnt(0)
	s_nop 3
	global_load_dword v0, v113, s[6:7] sc1
	s_waitcnt vmcnt(0)
	v_cmp_eq_u32_e32 vcc, v0, v1
	s_and_saveexec_b64 s[26:27], vcc
	s_cbranch_execz .LBB1_325
	s_mov_b32 s5, 1
	s_mov_b64 s[30:31], 0
	s_branch .LBB1_316

.LBB1_318:
	v_readlane_b32 s6, v254, 27
	v_readlane_b32 s7, v254, 28
	s_add_i32 s5, s5, 1
	s_mov_b64 s[40:41], -1
	s_nop 2
	global_load_dword v0, v113, s[6:7] sc1
	s_waitcnt vmcnt(0)
	v_cmp_ne_u32_e32 vcc, v0, v1
	s_orn2_b64 s[38:39], vcc, exec
	s_branch .LBB1_315

.LBB1_1285:
	v_readlane_b32 s6, v254, 21
	v_readlane_b32 s7, v254, 22
	v_cvt_f32_u32_e32 v1, v2
	v_sub_u32_e32 v4, 0, v2
	v_rcp_iflag_f32_e32 v1, v1
	s_nop 1
	global_atomic_add v3, v113, v215, s[6:7] sc0
	v_mul_f32_e32 v1, 0x4f7ffffe, v1
	v_cvt_u32_f32_e32 v1, v1
	v_mul_lo_u32 v4, v4, v1
	v_mul_hi_u32 v4, v1, v4
	v_add_u32_e32 v1, v1, v4
	s_waitcnt vmcnt(0)
	v_mul_hi_u32 v1, v3, v1
	v_mul_lo_u32 v4, v1, v2
	v_sub_u32_e32 v4, v3, v4
	v_add_u32_e32 v5, 1, v1
	v_cmp_ge_u32_e32 vcc, v4, v2
	v_add_u32_e32 v3, 1, v3
	s_nop 0
	v_cndmask_b32_e32 v1, v1, v5, vcc
	v_sub_u32_e32 v5, v4, v2
	v_cndmask_b32_e32 v4, v4, v5, vcc
	v_add_u32_e32 v5, 1, v1
	v_cmp_ge_u32_e32 vcc, v4, v2
	s_nop 1
	v_cndmask_b32_e32 v1, v1, v5, vcc
	v_mul_lo_u32 v4, v2, v1
	v_add_u32_e32 v2, v4, v2
	v_cmp_ne_u32_e32 vcc, v3, v2
	s_and_saveexec_b64 s[6:7], vcc
	s_xor_b64 s[16:17], exec, s[6:7]
	s_cbranch_execz .LBB1_1299
	v_readlane_b32 s6, v254, 27
	v_readlane_b32 s7, v254, 28
	s_waitcnt lgkmcnt(0)
	s_nop 3
	global_load_dword v0, v113, s[6:7] sc1
	s_waitcnt vmcnt(0)
	v_cmp_eq_u32_e32 vcc, v0, v1
	s_and_saveexec_b64 s[18:19], vcc
	s_cbranch_execz .LBB1_1298
	s_mov_b32 s1, 1
	s_mov_b64 s[26:27], 0
	s_branch .LBB1_1289

.LBB1_1291:
	v_readlane_b32 s6, v254, 27
	v_readlane_b32 s7, v254, 28
	s_add_i32 s1, s1, 1
	s_mov_b64 s[38:39], -1
	s_nop 2
	global_load_dword v0, v113, s[6:7] sc1
	s_waitcnt vmcnt(0)
	v_cmp_ne_u32_e32 vcc, v0, v1
	s_orn2_b64 s[36:37], vcc, exec
	s_branch .LBB1_1288
